# attention loop split into a steady loop without end-of-unit and diagonal-mask checks plus the general loop
# speedup vs baseline: 1.0065x; 1.0065x over previous
; __device__ __forceinline__ void attn_unit(const Args& a, int l, int b, int h, int R0, bool special, LAS unsigned char* lds, float kb, int wv, bool pre, bool hasn, int nb, int nh, int nR0) {
;     ...
;         for (; t + 1 < tw; t += 2) { ATT_BODY(t, pc0, pc1, pb0, pb1); ATT_BODY(t + 1, pb0, pb1, pc0, pc1); }
.Lfa_entry:
	v_mov_b32_e32 v210, 0
	v_mov_b32_e32 v211, 0
	v_mov_b32_e32 v212, 0
	v_mov_b32_e32 v213, 0
	v_mov_b32_e32 v214, 0
	v_mov_b32_e32 v215, 0
	v_mov_b32_e32 v216, 0
	v_mov_b32_e32 v217, 0
	v_mov_b32_e32 v218, 0
	v_mov_b32_e32 v219, 0
	v_mov_b32_e32 v220, 0
	v_mov_b32_e32 v221, 0
	v_mov_b32_e32 v222, 0
	v_mov_b32_e32 v223, 0
	v_mov_b32_e32 v224, 0
	v_mov_b32_e32 v225, 0
	v_mov_b32_e32 v234, 0
	v_mov_b32_e32 v235, 0
	v_mov_b32_e32 v236, 0
	v_mov_b32_e32 v237, 0
	v_mov_b32_e32 v238, 0
	v_mov_b32_e32 v239, 0
	v_mov_b32_e32 v240, 0
	v_mov_b32_e32 v241, 0
	v_mov_b32_e32 v248, 0
	v_mov_b32_e32 v249, 0
	v_mov_b32_e32 v250, 0
	v_mov_b32_e32 v251, 0
	s_mov_b32 s0, 0xd000
	v_add3_u32 v247, v26, v28, s0
	v_readfirstlane_b32 s22, v20
	v_readfirstlane_b32 s23, v21
	s_nop 1
	v_subrev_u32_e32 v0, s22, v20
	v_subrev_u32_e32 v14, s22, v18
	s_add_u32 s22, s22, 0x220c000
	s_addc_u32 s23, s23, 0
	v_readfirstlane_b32 s34, v22
	v_readfirstlane_b32 s35, v23
	s_nop 1
	v_subrev_u32_e32 v15, s34, v22
	v_subrev_u32_e32 v197, s34, v24
	s_add_u32 s34, s34, 0x1b900180
	s_addc_u32 s35, s35, 0
	s_and_b32 s88, s87, 3
	s_mulk_i32 s88, 0x3400
	s_add_i32 s90, s87, 1
	s_and_b32 s90, s90, 3
	s_mulk_i32 s90, 0x3400
	s_mov_b32 s32, 0
	s_movk_i32 s30, 0x2400
	s_mov_b32 s31, 0
	s_add_i32 s24, s77, -1
	s_add_i32 s0, s73, -3
	s_min_i32 s24, s24, s0
	s_add_i32 s0, s74, 1
	s_ashr_i32 s0, s0, 6
	s_min_i32 s24, s24, s0
	s_add_i32 s76, s87, 2
	s_cmp_le_i32 s76, s24
	s_cbranch_scc0 .Lfa_loop
.Lfa_sloop:
	s_add_i32 s76, s87, 2
	v_add_u32_e32 v230, s88, v190
	v_add_u32_e32 v231, s30, v247
	ds_read_b128 v[2:5], v230
	ds_read_b128 v[6:9], v230 offset:6656
	ds_read_b128 v[10:13], v230 offset:32
	ds_read_b128 v[198:201], v230 offset:6688
	ds_read_b128 v[202:205], v230 offset:64
	ds_read_b128 v[206:209], v230 offset:6720
	v_mfma_f32_32x32x16_bf16 v[64:79], v[210:213], v[234:237], v[64:79]
	v_exp_f32_e32 v96, v96
	v_exp_f32_e32 v97, v97
	v_add_f32_e32 v248, v248, v96
	v_exp_f32_e32 v98, v98
	v_mfma_f32_32x32x16_bf16 v[48:63], v[214:217], v[234:237], v[48:63]
	s_xor_b32 s1, s88, 0x6800
	s_add_i32 m0, s1, s66
	s_and_b64 vcc, exec, s[40:41]
	global_load_lds_dwordx4 v0, s[22:23]
	s_cbranch_vccnz .Lfa_as_nok
	s_add_i32 m0, s1, s78
	s_and_b64 vcc, exec, s[42:43]
	global_load_lds_dwordx4 v14, s[22:23]
.Lfa_as_nok:
	s_add_u32 s22, s22, 0x3000
	s_addc_u32 s23, s23, 0
	v_add_f32_e32 v249, v249, v97
	v_exp_f32_e32 v99, v99
	v_add_f32_e32 v250, v250, v98
	v_exp_f32_e32 v100, v100
	v_mfma_f32_32x32x16_bf16 v[64:79], v[218:221], v[238:241], v[64:79]
	ds_read_b128 v[210:213], v230 offset:96
	ds_read_b128 v[214:217], v230 offset:6752
	v_add_f32_e32 v251, v251, v99
	v_exp_f32_e32 v101, v101
	v_add_f32_e32 v248, v248, v100
	v_exp_f32_e32 v102, v102
	v_mfma_f32_32x32x16_bf16 v[48:63], v[222:225], v[238:241], v[48:63]
	ds_read_b128 v[218:221], v230 offset:128
	ds_read_b128 v[222:225], v230 offset:6784
	ds_read_b128 v[234:237], v230 offset:160
	ds_read_b128 v[238:241], v230 offset:6816
	s_add_i32 s1, s31, s66
	s_add_i32 m0, s1, 0xd000
	s_and_b64 vcc, exec, s[42:43]
	global_load_lds_dwordx4 v15, s[34:35]
	s_cbranch_vccnz .Lfa_as_nov
	s_add_i32 m0, s31, 0xf000
	s_nop 0
	global_load_lds_dwordx4 v197, s[34:35]
.Lfa_as_nov:
	s_add_u32 s34, s34, 0x80
	s_addc_u32 s35, s35, 0
	v_add_f32_e32 v249, v249, v101
	v_exp_f32_e32 v103, v103
	v_add_f32_e32 v250, v250, v102
	v_add_f32_e32 v251, v251, v103
	s_waitcnt lgkmcnt(10)
	v_mfma_f32_32x32x16_bf16 v[128:143], v[2:5], v[156:159], v[32:47]
	v_cvt_pk_bf16_f32 v96, v96, v97
	v_cvt_pk_bf16_f32 v97, v98, v99
	v_cvt_pk_bf16_f32 v98, v100, v101
	v_cvt_pk_bf16_f32 v99, v102, v103
	v_mfma_f32_32x32x16_bf16 v[112:127], v[6:9], v[156:159], v[32:47]
	ds_read_b128 v[2:5], v231
	ds_read_b128 v[6:9], v231 offset:4608
	v_exp_f32_e32 v104, v104
	v_exp_f32_e32 v105, v105
	v_add_f32_e32 v248, v248, v104
	v_exp_f32_e32 v106, v106
	s_waitcnt lgkmcnt(10)
	v_mfma_f32_32x32x16_bf16 v[128:143], v[10:13], v[160:163], v[128:143]
	v_add_f32_e32 v249, v249, v105
	v_exp_f32_e32 v107, v107
	v_add_f32_e32 v250, v250, v106
	v_exp_f32_e32 v108, v108
	v_mfma_f32_32x32x16_bf16 v[112:127], v[198:201], v[160:163], v[112:127]
	ds_read_b128 v[10:13], v231 offset:32
	ds_read_b128 v[198:201], v231 offset:4640
	v_add_f32_e32 v251, v251, v107
	v_exp_f32_e32 v109, v109
	v_add_f32_e32 v248, v248, v108
	v_exp_f32_e32 v110, v110
	s_waitcnt lgkmcnt(10)
	v_mfma_f32_32x32x16_bf16 v[128:143], v[202:205], v[164:167], v[128:143]
	v_add_f32_e32 v249, v249, v109
	v_exp_f32_e32 v111, v111
	v_add_f32_e32 v250, v250, v110
	v_add_f32_e32 v251, v251, v111
	v_mfma_f32_32x32x16_bf16 v[112:127], v[206:209], v[164:167], v[112:127]
	v_cvt_pk_bf16_f32 v104, v104, v105
	v_cvt_pk_bf16_f32 v105, v106, v107
	v_cvt_pk_bf16_f32 v106, v108, v109
	v_cvt_pk_bf16_f32 v107, v110, v111
	s_waitcnt lgkmcnt(8)
	v_mfma_f32_32x32x16_bf16 v[128:143], v[210:213], v[144:147], v[128:143]
	v_exp_f32_e32 v80, v80
	v_exp_f32_e32 v81, v81
	v_add_f32_e32 v248, v248, v80
	v_exp_f32_e32 v82, v82
	v_mfma_f32_32x32x16_bf16 v[112:127], v[214:217], v[144:147], v[112:127]
	ds_read_b128 v[210:213], v231 offset:64
	ds_read_b128 v[214:217], v231 offset:4672
	v_add_f32_e32 v249, v249, v81
	v_exp_f32_e32 v83, v83
	v_add_f32_e32 v250, v250, v82
	v_exp_f32_e32 v84, v84
	s_waitcnt lgkmcnt(8)
	v_mfma_f32_32x32x16_bf16 v[128:143], v[218:221], v[148:151], v[128:143]
	v_add_f32_e32 v251, v251, v83
	v_exp_f32_e32 v85, v85
	v_add_f32_e32 v248, v248, v84
	v_exp_f32_e32 v86, v86
	v_mfma_f32_32x32x16_bf16 v[112:127], v[222:225], v[148:151], v[112:127]
	ds_read_b128 v[218:221], v231 offset:96
	ds_read_b128 v[222:225], v231 offset:4704
	v_add_f32_e32 v249, v249, v85
	v_exp_f32_e32 v87, v87
	v_add_f32_e32 v250, v250, v86
	v_add_f32_e32 v251, v251, v87
	s_waitcnt lgkmcnt(8)
	v_mfma_f32_32x32x16_bf16 v[128:143], v[234:237], v[152:155], v[128:143]
	v_exp_f32_e32 v88, v88
	v_exp_f32_e32 v89, v89
	v_add_f32_e32 v248, v248, v88
	v_exp_f32_e32 v90, v90
	v_mfma_f32_32x32x16_bf16 v[112:127], v[238:241], v[152:155], v[112:127]
	v_add_f32_e32 v249, v249, v89
	v_exp_f32_e32 v91, v91
	v_add_f32_e32 v250, v250, v90
	v_exp_f32_e32 v92, v92
	s_waitcnt lgkmcnt(6)
	v_mfma_f32_32x32x16_bf16 v[64:79], v[2:5], v[96:99], v[64:79]
	v_add_f32_e32 v251, v251, v91
	v_exp_f32_e32 v93, v93
	v_add_f32_e32 v248, v248, v92
	v_exp_f32_e32 v94, v94
	v_mfma_f32_32x32x16_bf16 v[48:63], v[6:9], v[96:99], v[48:63]
	v_add_f32_e32 v249, v249, v93
	v_exp_f32_e32 v95, v95
	v_add_f32_e32 v250, v250, v94
	v_add_f32_e32 v251, v251, v95
	s_waitcnt lgkmcnt(4)
	v_mfma_f32_32x32x16_bf16 v[64:79], v[10:13], v[104:107], v[64:79]
	v_cvt_pk_bf16_f32 v234, v80, v81
	v_cvt_pk_bf16_f32 v235, v82, v83
	v_cvt_pk_bf16_f32 v236, v84, v85
	v_cvt_pk_bf16_f32 v237, v86, v87
	v_mfma_f32_32x32x16_bf16 v[48:63], v[198:201], v[104:107], v[48:63]
	v_cvt_pk_bf16_f32 v238, v88, v89
	v_cvt_pk_bf16_f32 v239, v90, v91
	v_cvt_pk_bf16_f32 v240, v92, v93
	v_cvt_pk_bf16_f32 v241, v94, v95
	s_mov_b32 s1, s30
	s_add_i32 s30, s30, 0x2400
	s_cmp_eq_u32 s30, 0x6c00
	s_cselect_b32 s30, 0, s30
	s_mov_b32 s31, s1
	s_cmp_eq_u32 s75, 3
	s_cbranch_scc1 .Lfa_as_w3
	s_cmp_eq_u32 s75, 2
	s_cbranch_scc1 .Lfa_as_w2
	s_waitcnt vmcnt(4)
	s_branch .Lfa_as_wj

.Lfa_as_wj:
	s_waitcnt lgkmcnt(0)
	s_barrier
	v_add_u32_e32 v230, s90, v190
	v_add_u32_e32 v231, s30, v247
	ds_read_b128 v[2:5], v230
	ds_read_b128 v[6:9], v230 offset:6656
	ds_read_b128 v[10:13], v230 offset:32
	ds_read_b128 v[198:201], v230 offset:6688
	ds_read_b128 v[202:205], v230 offset:64
	ds_read_b128 v[206:209], v230 offset:6720
	v_mfma_f32_32x32x16_bf16 v[64:79], v[210:213], v[234:237], v[64:79]
	v_exp_f32_e32 v128, v128
	v_exp_f32_e32 v129, v129
	v_add_f32_e32 v248, v248, v128
	v_exp_f32_e32 v130, v130
	v_mfma_f32_32x32x16_bf16 v[48:63], v[214:217], v[234:237], v[48:63]
	s_xor_b32 s1, s90, 0xa800
	s_add_i32 m0, s1, s66
	s_and_b64 vcc, exec, s[40:41]
	global_load_lds_dwordx4 v0, s[22:23]
	s_cbranch_vccnz .Lfa_bs_nok
	s_add_i32 m0, s1, s78
	s_and_b64 vcc, exec, s[42:43]
	global_load_lds_dwordx4 v14, s[22:23]
.Lfa_bs_nok:
	s_add_u32 s22, s22, 0x3000
	s_addc_u32 s23, s23, 0
	v_add_f32_e32 v249, v249, v129
	v_exp_f32_e32 v131, v131
	v_add_f32_e32 v250, v250, v130
	v_exp_f32_e32 v132, v132
	v_mfma_f32_32x32x16_bf16 v[64:79], v[218:221], v[238:241], v[64:79]
	ds_read_b128 v[210:213], v230 offset:96
	ds_read_b128 v[214:217], v230 offset:6752
	v_add_f32_e32 v251, v251, v131
	v_exp_f32_e32 v133, v133
	v_add_f32_e32 v248, v248, v132
	v_exp_f32_e32 v134, v134
	v_mfma_f32_32x32x16_bf16 v[48:63], v[222:225], v[238:241], v[48:63]
	ds_read_b128 v[218:221], v230 offset:128
	ds_read_b128 v[222:225], v230 offset:6784
	ds_read_b128 v[234:237], v230 offset:160
	ds_read_b128 v[238:241], v230 offset:6816
	s_add_i32 s1, s31, s66
	s_add_i32 m0, s1, 0xd000
	s_and_b64 vcc, exec, s[42:43]
	global_load_lds_dwordx4 v15, s[34:35]
	s_cbranch_vccnz .Lfa_bs_nov
	s_add_i32 m0, s31, 0xf000
	s_nop 0
	global_load_lds_dwordx4 v197, s[34:35]
.Lfa_bs_nov:
	s_add_u32 s34, s34, 0x80
	s_addc_u32 s35, s35, 0
	v_add_f32_e32 v249, v249, v133
	v_exp_f32_e32 v135, v135
	v_add_f32_e32 v250, v250, v134
	v_add_f32_e32 v251, v251, v135
	s_waitcnt lgkmcnt(10)
	v_mfma_f32_32x32x16_bf16 v[96:111], v[2:5], v[156:159], v[32:47]
	v_cvt_pk_bf16_f32 v128, v128, v129
	v_cvt_pk_bf16_f32 v129, v130, v131
	v_cvt_pk_bf16_f32 v130, v132, v133
	v_cvt_pk_bf16_f32 v131, v134, v135
	v_mfma_f32_32x32x16_bf16 v[80:95], v[6:9], v[156:159], v[32:47]
	ds_read_b128 v[2:5], v231
	ds_read_b128 v[6:9], v231 offset:4608
	v_exp_f32_e32 v136, v136
	v_exp_f32_e32 v137, v137
	v_add_f32_e32 v248, v248, v136
	v_exp_f32_e32 v138, v138
	s_waitcnt lgkmcnt(10)
	v_mfma_f32_32x32x16_bf16 v[96:111], v[10:13], v[160:163], v[96:111]
	v_add_f32_e32 v249, v249, v137
	v_exp_f32_e32 v139, v139
	v_add_f32_e32 v250, v250, v138
	v_exp_f32_e32 v140, v140
	v_mfma_f32_32x32x16_bf16 v[80:95], v[198:201], v[160:163], v[80:95]
	ds_read_b128 v[10:13], v231 offset:32
	ds_read_b128 v[198:201], v231 offset:4640
	v_add_f32_e32 v251, v251, v139
	v_exp_f32_e32 v141, v141
	v_add_f32_e32 v248, v248, v140
	v_exp_f32_e32 v142, v142
	s_waitcnt lgkmcnt(10)
	v_mfma_f32_32x32x16_bf16 v[96:111], v[202:205], v[164:167], v[96:111]
	v_add_f32_e32 v249, v249, v141
	v_exp_f32_e32 v143, v143
	v_add_f32_e32 v250, v250, v142
	v_add_f32_e32 v251, v251, v143
	v_mfma_f32_32x32x16_bf16 v[80:95], v[206:209], v[164:167], v[80:95]
	v_cvt_pk_bf16_f32 v136, v136, v137
	v_cvt_pk_bf16_f32 v137, v138, v139
	v_cvt_pk_bf16_f32 v138, v140, v141
	v_cvt_pk_bf16_f32 v139, v142, v143
	s_waitcnt lgkmcnt(8)
	v_mfma_f32_32x32x16_bf16 v[96:111], v[210:213], v[144:147], v[96:111]
	v_exp_f32_e32 v112, v112
	v_exp_f32_e32 v113, v113
	v_add_f32_e32 v248, v248, v112
	v_exp_f32_e32 v114, v114
	v_mfma_f32_32x32x16_bf16 v[80:95], v[214:217], v[144:147], v[80:95]
	ds_read_b128 v[210:213], v231 offset:64
	ds_read_b128 v[214:217], v231 offset:4672
	v_add_f32_e32 v249, v249, v113
	v_exp_f32_e32 v115, v115
	v_add_f32_e32 v250, v250, v114
	v_exp_f32_e32 v116, v116
	s_waitcnt lgkmcnt(8)
	v_mfma_f32_32x32x16_bf16 v[96:111], v[218:221], v[148:151], v[96:111]
	v_add_f32_e32 v251, v251, v115
	v_exp_f32_e32 v117, v117
	v_add_f32_e32 v248, v248, v116
	v_exp_f32_e32 v118, v118
	v_mfma_f32_32x32x16_bf16 v[80:95], v[222:225], v[148:151], v[80:95]
	ds_read_b128 v[218:221], v231 offset:96
	ds_read_b128 v[222:225], v231 offset:4704
	v_add_f32_e32 v249, v249, v117
	v_exp_f32_e32 v119, v119
	v_add_f32_e32 v250, v250, v118
	v_add_f32_e32 v251, v251, v119
	s_waitcnt lgkmcnt(8)
	v_mfma_f32_32x32x16_bf16 v[96:111], v[234:237], v[152:155], v[96:111]
	v_exp_f32_e32 v120, v120
	v_exp_f32_e32 v121, v121
	v_add_f32_e32 v248, v248, v120
	v_exp_f32_e32 v122, v122
	v_mfma_f32_32x32x16_bf16 v[80:95], v[238:241], v[152:155], v[80:95]
	v_add_f32_e32 v249, v249, v121
	v_exp_f32_e32 v123, v123
	v_add_f32_e32 v250, v250, v122
	v_exp_f32_e32 v124, v124
	s_waitcnt lgkmcnt(6)
	v_mfma_f32_32x32x16_bf16 v[64:79], v[2:5], v[128:131], v[64:79]
	v_add_f32_e32 v251, v251, v123
	v_exp_f32_e32 v125, v125
	v_add_f32_e32 v248, v248, v124
	v_exp_f32_e32 v126, v126
	v_mfma_f32_32x32x16_bf16 v[48:63], v[6:9], v[128:131], v[48:63]
	v_add_f32_e32 v249, v249, v125
	v_exp_f32_e32 v127, v127
	v_add_f32_e32 v250, v250, v126
	v_add_f32_e32 v251, v251, v127
	s_waitcnt lgkmcnt(4)
	v_mfma_f32_32x32x16_bf16 v[64:79], v[10:13], v[136:139], v[64:79]
	v_cvt_pk_bf16_f32 v234, v112, v113
	v_cvt_pk_bf16_f32 v235, v114, v115
	v_cvt_pk_bf16_f32 v236, v116, v117
	v_cvt_pk_bf16_f32 v237, v118, v119
	v_mfma_f32_32x32x16_bf16 v[48:63], v[198:201], v[136:139], v[48:63]
	v_cvt_pk_bf16_f32 v238, v120, v121
	v_cvt_pk_bf16_f32 v239, v122, v123
	v_cvt_pk_bf16_f32 v240, v124, v125
	v_cvt_pk_bf16_f32 v241, v126, v127
	s_mov_b32 s1, s30
	s_add_i32 s30, s30, 0x2400
	s_cmp_eq_u32 s30, 0x6c00
	s_cselect_b32 s30, 0, s30
	s_mov_b32 s31, s1
	s_cmp_eq_u32 s75, 3
	s_cbranch_scc1 .Lfa_bs_w3
	s_cmp_eq_u32 s75, 2
	s_cbranch_scc1 .Lfa_bs_w2
	s_waitcnt vmcnt(4)
	s_branch .Lfa_bs_wj

; __device__ __forceinline__ void attn_unit(const Args& a, int l, int b, int h, int R0, bool special, LAS unsigned char* lds, float kb, int wv, bool pre, bool hasn, int nb, int nh, int nR0) {
;     ...
;         for (; t + 1 < tw; t += 2) { ATT_BODY(t, pc0, pc1, pb0, pb1); ATT_BODY(t + 1, pb0, pb1, pc0, pc1); }
.Lfa_bs_wj:
	s_waitcnt lgkmcnt(0)
	s_barrier
	s_addk_i32 s83, 0x4800
	s_addk_i32 s84, 0x80
	s_addk_i32 s85, 0x4800
	s_add_i32 s79, s79, 2
	s_add_i32 s86, s86, 2
	s_add_i32 s80, s80, 2
	s_add_i32 s32, s32, 1
	s_xor_b32 s88, s88, 0x6800
	s_xor_b32 s90, s90, 0xa800
	s_mov_b32 s87, s76
	s_add_i32 s0, s76, 2
	s_cmp_le_i32 s0, s24
	s_cbranch_scc1 .Lfa_sloop
	s_cmp_lt_i32 s76, s77
	s_cbranch_scc0 .Lfa_exit
